# GDN loop with immediate LDS offsets (per-iteration bases) on top of the guarded idle-tail converter
# baseline (speedup 1.0000x reference)
; #define LAS __attribute__((address_space(3)))
; template <int CTRL> __device__ __forceinline__ float dppf(float x) { return __builtin_bit_cast(float, __builtin_amdgcn_update_dpp(0, __builtin_bit_cast(int, x), CTRL, 0xF, 0xF, true)); }
; __device__ __forceinline__ float red16(float x) { x = red8(x); x += dppf<0x140>(x); return x; }
; __device__ __forceinline__ void gdn_group8(float (&S)[4], float (&pp)[16], int j0, const LAS float* L, int sbase_, int kg, int vl) {
;     typedef RecCfg<1> C;
;     f32x4 q[8], k[8]; f32x2 sc[8]; float v[8];
; #pragma unroll
;     for (int j = 0; j < 8; ++j) { const int s = sbase_ + j;
;         q[j] = *(const LAS f32x4*)(L + C::OFF_Q + s * 64 + kg * 4); k[j] = *(const LAS f32x4*)(L + C::OFF_K + s * 64 + kg * 4);
;         sc[j] = *(const LAS f32x2*)(L + C::OFF_SC + s * 4); v[j] = L[C::OFF_V + s * 32 + vl]; }
;     __builtin_amdgcn_sched_barrier(0);
;     f32x2 s0 = (f32x2){S[0], S[1]}, s1 = (f32x2){S[2], S[3]};
; #pragma unroll
;     for (int j = 0; j < 8; ++j) {
;         const f32x2 k0 = (f32x2){k[j][0], k[j][1]}, k1 = (f32x2){k[j][2], k[j][3]};
;         f32x2 r2 = s0 * k0; r2 = s1 * k1 + r2;
;         const float r = red16(r2.x + r2.y);
;         const float u = sc[j][1] * (v[j] - sc[j][0] * r);
;         const f32x2 uu = (f32x2){u, u}, aa = (f32x2){sc[j][0], sc[j][0]};
;         s0 = s0 * aa + k0 * uu; s1 = s1 * aa + k1 * uu;
;         f32x2 p2 = s0 * (f32x2){q[j][0], q[j][1]}; p2 = s1 * (f32x2){q[j][2], q[j][3]} + p2;
;         pp[j0 + j] = p2.x + p2.y;
;     }
;     S[0] = s0.x; S[1] = s0.y; S[2] = s1.x; S[3] = s1.y;
; }
; __device__ __forceinline__ float reduce_scatter16(const float (&p)[16], int kg) {
;     const bool b3 = kg & 8, b2 = kg & 4, b1 = kg & 2, b0 = kg & 1;
;     float t[8], u[4], w[2];
; #pragma unroll
;     for (int j = 0; j < 8; ++j) { const float keep = b3 ? p[j + 8] : p[j], send = b3 ? p[j] : p[j + 8]; t[j] = keep + dppf<0x140>(send); }
; #pragma unroll
;     for (int j = 0; j < 4; ++j) { const float keep = b2 ? t[j + 4] : t[j], send = b2 ? t[j] : t[j + 4]; u[j] = keep + dppf<0x141>(send); }
; #pragma unroll
;     for (int j = 0; j < 2; ++j) { const float keep = b1 ? u[j + 2] : u[j], send = b1 ? u[j] : u[j + 2]; w[j] = keep + dppf<0x1B>(send); }
;     const float keep = b0 ? w[1] : w[0], send = b0 ? w[0] : w[1];
;     return keep + dppf<0xB1>(send);
; }
.LBB0_411:
	s_lshl_b32 s5, s22, 2
	s_mov_b32 s8, 4
	s_add_i32 s2, s17, s5
	v_add_u32_e32 v172, s5, v26
	v_add_u32_e32 v173, s5, v25
	v_mov_b32_e32 v174, s2
	v_bfrev_b32_e32 v175, v20
	s_movk_i32 s3, 0x4400
	v_lshrrev_b32_e32 v175, 28, v175
	v_lshlrev_b32_e32 v175, 7, v175
	v_add3_u32 v175, v175, v173, s3
	ds_read_b128 v[28:31], v172 offset:0
	ds_read_b128 v[32:35], v172 offset:16384
	ds_read_b128 v[36:39], v172 offset:256
	ds_read_b128 v[40:43], v172 offset:16640
	ds_read_b128 v[44:47], v172 offset:512
	ds_read_b128 v[48:51], v172 offset:16896
	ds_read_b128 v[52:55], v172 offset:768
	ds_read_b128 v[56:59], v172 offset:17152
	ds_read2_b32 v[60:61], v173 offset1:32
	ds_read2_b32 v[62:63], v173 offset0:64 offset1:96
	ds_read2_b64 v[64:67], v174 offset0:0 offset1:2
	ds_read2_b64 v[68:71], v174 offset0:4 offset1:6
	v_add_u32_e32 v173, 0x200, v173
.Lgdn_step_loop:
	s_waitcnt lgkmcnt(0)
	v_pk_mul_f32 v[158:159], v[10:11], v[32:33]
	v_pk_mul_f32 v[160:161], v[10:11], v[64:65] op_sel_hi:[1,0]
	v_pk_fma_f32 v[158:159], v[12:13], v[34:35], v[158:159]
	v_pk_mul_f32 v[162:163], v[12:13], v[64:65] op_sel_hi:[1,0]
	v_add_f32_e32 v168, v158, v159
	ds_read2_b32 v[104:105], v173 offset1:32
	ds_read2_b32 v[106:107], v173 offset0:64 offset1:96
	v_add_f32_dpp v168, v168, v168 quad_perm:[1,0,3,2] row_mask:0xf bank_mask:0xf bound_ctrl:1
	ds_read_b128 v[72:75], v172 offset:1024
	ds_read_b128 v[76:79], v172 offset:17408
	v_add_f32_dpp v168, v168, v168 quad_perm:[2,3,0,1] row_mask:0xf bank_mask:0xf bound_ctrl:1
	ds_read_b128 v[80:83], v172 offset:1280
	ds_read_b128 v[84:87], v172 offset:17664
	v_add_f32_dpp v168, v168, v168 row_half_mirror row_mask:0xf bank_mask:0xf bound_ctrl:1
	ds_read_b128 v[88:91], v172 offset:1536
	ds_read_b128 v[92:95], v172 offset:17920
	v_add_f32_dpp v168, v168, v168 row_mirror row_mask:0xf bank_mask:0xf bound_ctrl:1
	v_fma_f32 v170, -v64, v168, v60
	v_mul_f32_e32 v170, v65, v170
	v_pk_fma_f32 v[10:11], v[32:33], v[170:171], v[160:161] op_sel_hi:[1,0,1]
	v_pk_fma_f32 v[12:13], v[34:35], v[170:171], v[162:163] op_sel_hi:[1,0,1]
	v_pk_mul_f32 v[158:159], v[10:11], v[40:41]
	v_pk_mul_f32 v[160:161], v[10:11], v[66:67] op_sel_hi:[1,0]
	v_pk_fma_f32 v[158:159], v[12:13], v[42:43], v[158:159]
	v_pk_mul_f32 v[162:163], v[12:13], v[66:67] op_sel_hi:[1,0]
	v_add_f32_e32 v168, v158, v159
	v_pk_mul_f32 v[164:165], v[28:29], v[10:11]
	ds_read_b128 v[96:99], v172 offset:1792
	v_add_f32_dpp v168, v168, v168 quad_perm:[1,0,3,2] row_mask:0xf bank_mask:0xf bound_ctrl:1
	v_pk_fma_f32 v[164:165], v[30:31], v[12:13], v[164:165]
	ds_read_b128 v[100:103], v172 offset:18176
	v_add_f32_dpp v168, v168, v168 quad_perm:[2,3,0,1] row_mask:0xf bank_mask:0xf bound_ctrl:1
	v_add_f32_e32 v116, v164, v165
	ds_read2_b64 v[108:111], v174 offset0:8 offset1:10
	v_add_f32_dpp v168, v168, v168 row_half_mirror row_mask:0xf bank_mask:0xf bound_ctrl:1
	ds_read2_b64 v[112:115], v174 offset0:12 offset1:14
	v_add_u32_e32 v173, 0x200, v173
	v_add_f32_dpp v168, v168, v168 row_mirror row_mask:0xf bank_mask:0xf bound_ctrl:1
	v_fma_f32 v170, -v66, v168, v61
	v_mul_f32_e32 v170, v67, v170
	v_pk_fma_f32 v[10:11], v[40:41], v[170:171], v[160:161] op_sel_hi:[1,0,1]
	v_pk_fma_f32 v[12:13], v[42:43], v[170:171], v[162:163] op_sel_hi:[1,0,1]
	v_pk_mul_f32 v[158:159], v[10:11], v[48:49]
	v_pk_mul_f32 v[160:161], v[10:11], v[68:69] op_sel_hi:[1,0]
	v_pk_fma_f32 v[158:159], v[12:13], v[50:51], v[158:159]
	v_pk_mul_f32 v[162:163], v[12:13], v[68:69] op_sel_hi:[1,0]
	v_add_f32_e32 v168, v158, v159
	v_pk_mul_f32 v[166:167], v[36:37], v[10:11]
	v_add_f32_dpp v140, v116, v116 row_mirror row_mask:0xf bank_mask:0x3 bound_ctrl:1
	v_add_f32_dpp v168, v168, v168 quad_perm:[1,0,3,2] row_mask:0xf bank_mask:0xf bound_ctrl:1
	v_pk_fma_f32 v[166:167], v[38:39], v[12:13], v[166:167]
	s_add_i32 s8, s8, -1
	v_add_f32_dpp v168, v168, v168 quad_perm:[2,3,0,1] row_mask:0xf bank_mask:0xf bound_ctrl:1
	v_add_f32_e32 v117, v166, v167
	s_nop 0
	v_add_f32_dpp v168, v168, v168 row_half_mirror row_mask:0xf bank_mask:0xf bound_ctrl:1
	v_add_f32_dpp v140, v117, v117 row_mirror row_mask:0xf bank_mask:0xc bound_ctrl:1
	s_nop 0
	v_add_f32_dpp v168, v168, v168 row_mirror row_mask:0xf bank_mask:0xf bound_ctrl:1
	v_fma_f32 v170, -v68, v168, v62
	v_mul_f32_e32 v170, v69, v170
	v_pk_fma_f32 v[10:11], v[48:49], v[170:171], v[160:161] op_sel_hi:[1,0,1]
	v_pk_fma_f32 v[12:13], v[50:51], v[170:171], v[162:163] op_sel_hi:[1,0,1]
	v_pk_mul_f32 v[158:159], v[10:11], v[56:57]
	v_pk_mul_f32 v[160:161], v[10:11], v[70:71] op_sel_hi:[1,0]
	v_pk_fma_f32 v[158:159], v[12:13], v[58:59], v[158:159]
	v_pk_mul_f32 v[162:163], v[12:13], v[70:71] op_sel_hi:[1,0]
	v_add_f32_e32 v168, v158, v159
	v_pk_mul_f32 v[164:165], v[44:45], v[10:11]
	v_add_f32_dpp v148, v140, v140 row_half_mirror row_mask:0xf bank_mask:0x5 bound_ctrl:1
	v_add_f32_dpp v168, v168, v168 quad_perm:[1,0,3,2] row_mask:0xf bank_mask:0xf bound_ctrl:1
	v_pk_fma_f32 v[164:165], v[46:47], v[12:13], v[164:165]
	s_nop 0
	v_add_f32_dpp v168, v168, v168 quad_perm:[2,3,0,1] row_mask:0xf bank_mask:0xf bound_ctrl:1
	v_add_f32_e32 v118, v164, v165
	s_nop 0
	v_add_f32_dpp v168, v168, v168 row_half_mirror row_mask:0xf bank_mask:0xf bound_ctrl:1
	v_add_f32_dpp v141, v118, v118 row_mirror row_mask:0xf bank_mask:0x3 bound_ctrl:1
	s_nop 0
	v_add_f32_dpp v168, v168, v168 row_mirror row_mask:0xf bank_mask:0xf bound_ctrl:1
	v_fma_f32 v170, -v70, v168, v63
	v_mul_f32_e32 v170, v71, v170
	v_pk_fma_f32 v[10:11], v[56:57], v[170:171], v[160:161] op_sel_hi:[1,0,1]
	v_pk_fma_f32 v[12:13], v[58:59], v[170:171], v[162:163] op_sel_hi:[1,0,1]
	s_waitcnt lgkmcnt(0)
; #define LAS __attribute__((address_space(3)))
; template <int CTRL> __device__ __forceinline__ float dppf(float x) { return __builtin_bit_cast(float, __builtin_amdgcn_update_dpp(0, __builtin_bit_cast(int, x), CTRL, 0xF, 0xF, true)); }
; __device__ __forceinline__ float red16(float x) { x = red8(x); x += dppf<0x140>(x); return x; }
; __device__ __forceinline__ void gdn_group8(float (&S)[4], float (&pp)[16], int j0, const LAS float* L, int sbase_, int kg, int vl) {
;     typedef RecCfg<1> C;
;     f32x4 q[8], k[8]; f32x2 sc[8]; float v[8];
; #pragma unroll
;     for (int j = 0; j < 8; ++j) { const int s = sbase_ + j;
;         q[j] = *(const LAS f32x4*)(L + C::OFF_Q + s * 64 + kg * 4); k[j] = *(const LAS f32x4*)(L + C::OFF_K + s * 64 + kg * 4);
;         sc[j] = *(const LAS f32x2*)(L + C::OFF_SC + s * 4); v[j] = L[C::OFF_V + s * 32 + vl]; }
;     __builtin_amdgcn_sched_barrier(0);
;     f32x2 s0 = (f32x2){S[0], S[1]}, s1 = (f32x2){S[2], S[3]};
; #pragma unroll
;     for (int j = 0; j < 8; ++j) {
;         const f32x2 k0 = (f32x2){k[j][0], k[j][1]}, k1 = (f32x2){k[j][2], k[j][3]};
;         f32x2 r2 = s0 * k0; r2 = s1 * k1 + r2;
;         const float r = red16(r2.x + r2.y);
;         const float u = sc[j][1] * (v[j] - sc[j][0] * r);
;         const f32x2 uu = (f32x2){u, u}, aa = (f32x2){sc[j][0], sc[j][0]};
;         s0 = s0 * aa + k0 * uu; s1 = s1 * aa + k1 * uu;
;         f32x2 p2 = s0 * (f32x2){q[j][0], q[j][1]}; p2 = s1 * (f32x2){q[j][2], q[j][3]} + p2;
;         pp[j0 + j] = p2.x + p2.y;
;     }
;     S[0] = s0.x; S[1] = s0.y; S[2] = s1.x; S[3] = s1.y;
; }
; __device__ __forceinline__ float reduce_scatter16(const float (&p)[16], int kg) {
;     const bool b3 = kg & 8, b2 = kg & 4, b1 = kg & 2, b0 = kg & 1;
;     float t[8], u[4], w[2];
; #pragma unroll
;     for (int j = 0; j < 8; ++j) { const float keep = b3 ? p[j + 8] : p[j], send = b3 ? p[j] : p[j + 8]; t[j] = keep + dppf<0x140>(send); }
; #pragma unroll
;     for (int j = 0; j < 4; ++j) { const float keep = b2 ? t[j + 4] : t[j], send = b2 ? t[j] : t[j + 4]; u[j] = keep + dppf<0x141>(send); }
; #pragma unroll
;     for (int j = 0; j < 2; ++j) { const float keep = b1 ? u[j + 2] : u[j], send = b1 ? u[j] : u[j + 2]; w[j] = keep + dppf<0x1B>(send); }
;     const float keep = b0 ? w[1] : w[0], send = b0 ? w[0] : w[1];
;     return keep + dppf<0xB1>(send);
; }
	v_pk_mul_f32 v[158:159], v[10:11], v[76:77]
	v_pk_mul_f32 v[160:161], v[10:11], v[108:109] op_sel_hi:[1,0]
	v_pk_fma_f32 v[158:159], v[12:13], v[78:79], v[158:159]
	v_pk_mul_f32 v[162:163], v[12:13], v[108:109] op_sel_hi:[1,0]
	v_add_f32_e32 v168, v158, v159
	v_pk_mul_f32 v[166:167], v[52:53], v[10:11]
	s_nop 0
	v_add_f32_dpp v168, v168, v168 quad_perm:[1,0,3,2] row_mask:0xf bank_mask:0xf bound_ctrl:1
	v_pk_fma_f32 v[166:167], v[54:55], v[12:13], v[166:167]
	ds_read2_b32 v[60:61], v173 offset1:32
	v_add_f32_dpp v168, v168, v168 quad_perm:[2,3,0,1] row_mask:0xf bank_mask:0xf bound_ctrl:1
	v_add_f32_e32 v119, v166, v167
	ds_read2_b32 v[62:63], v173 offset0:64 offset1:96
	v_add_f32_dpp v168, v168, v168 row_half_mirror row_mask:0xf bank_mask:0xf bound_ctrl:1
	ds_read_b128 v[28:31], v172 offset:2048
	ds_read_b128 v[32:35], v172 offset:18432
	v_add_f32_dpp v168, v168, v168 row_mirror row_mask:0xf bank_mask:0xf bound_ctrl:1
	v_fma_f32 v170, -v108, v168, v104
	v_mul_f32_e32 v170, v109, v170
	v_pk_fma_f32 v[10:11], v[76:77], v[170:171], v[160:161] op_sel_hi:[1,0,1]
	v_pk_fma_f32 v[12:13], v[78:79], v[170:171], v[162:163] op_sel_hi:[1,0,1]
	v_pk_mul_f32 v[158:159], v[10:11], v[84:85]
	v_pk_mul_f32 v[160:161], v[10:11], v[110:111] op_sel_hi:[1,0]
	v_pk_fma_f32 v[158:159], v[12:13], v[86:87], v[158:159]
	v_pk_mul_f32 v[162:163], v[12:13], v[110:111] op_sel_hi:[1,0]
	v_add_f32_e32 v168, v158, v159
	v_pk_mul_f32 v[164:165], v[72:73], v[10:11]
	ds_read_b128 v[36:39], v172 offset:2304
	v_add_f32_dpp v168, v168, v168 quad_perm:[1,0,3,2] row_mask:0xf bank_mask:0xf bound_ctrl:1
	v_pk_fma_f32 v[164:165], v[74:75], v[12:13], v[164:165]
	ds_read_b128 v[40:43], v172 offset:18688
	v_add_f32_dpp v168, v168, v168 quad_perm:[2,3,0,1] row_mask:0xf bank_mask:0xf bound_ctrl:1
	v_add_f32_e32 v120, v164, v165
	ds_read_b128 v[44:47], v172 offset:2560
	v_add_f32_dpp v168, v168, v168 row_half_mirror row_mask:0xf bank_mask:0xf bound_ctrl:1
	ds_read_b128 v[48:51], v172 offset:18944
	ds_read_b128 v[52:55], v172 offset:2816
	v_add_f32_dpp v168, v168, v168 row_mirror row_mask:0xf bank_mask:0xf bound_ctrl:1
	v_fma_f32 v170, -v110, v168, v105
	v_mul_f32_e32 v170, v111, v170
	v_pk_fma_f32 v[10:11], v[84:85], v[170:171], v[160:161] op_sel_hi:[1,0,1]
	v_pk_fma_f32 v[12:13], v[86:87], v[170:171], v[162:163] op_sel_hi:[1,0,1]
	v_pk_mul_f32 v[158:159], v[10:11], v[92:93]
	v_pk_mul_f32 v[160:161], v[10:11], v[112:113] op_sel_hi:[1,0]
	v_pk_fma_f32 v[158:159], v[12:13], v[94:95], v[158:159]
	v_pk_mul_f32 v[162:163], v[12:13], v[112:113] op_sel_hi:[1,0]
	v_add_f32_e32 v168, v158, v159
	v_pk_mul_f32 v[166:167], v[80:81], v[10:11]
	ds_read_b128 v[56:59], v172 offset:19200
	v_add_f32_dpp v168, v168, v168 quad_perm:[1,0,3,2] row_mask:0xf bank_mask:0xf bound_ctrl:1
	v_pk_fma_f32 v[166:167], v[82:83], v[12:13], v[166:167]
	ds_read2_b64 v[64:67], v174 offset0:16 offset1:18
	v_add_f32_dpp v168, v168, v168 quad_perm:[2,3,0,1] row_mask:0xf bank_mask:0xf bound_ctrl:1
	v_add_f32_e32 v121, v166, v167
	ds_read2_b64 v[68:71], v174 offset0:20 offset1:22
	v_add_f32_dpp v168, v168, v168 row_half_mirror row_mask:0xf bank_mask:0xf bound_ctrl:1
	v_add_u32_e32 v173, 0x200, v173
	v_add_f32_dpp v142, v120, v120 row_mirror row_mask:0xf bank_mask:0x3 bound_ctrl:1
	v_add_f32_dpp v168, v168, v168 row_mirror row_mask:0xf bank_mask:0xf bound_ctrl:1
	v_fma_f32 v170, -v112, v168, v106
	v_mul_f32_e32 v170, v113, v170
	v_pk_fma_f32 v[10:11], v[92:93], v[170:171], v[160:161] op_sel_hi:[1,0,1]
	v_pk_fma_f32 v[12:13], v[94:95], v[170:171], v[162:163] op_sel_hi:[1,0,1]
	v_pk_mul_f32 v[158:159], v[10:11], v[100:101]
	v_pk_mul_f32 v[160:161], v[10:11], v[114:115] op_sel_hi:[1,0]
	v_pk_fma_f32 v[158:159], v[12:13], v[102:103], v[158:159]
	v_pk_mul_f32 v[162:163], v[12:13], v[114:115] op_sel_hi:[1,0]
	v_add_f32_e32 v168, v158, v159
	v_pk_mul_f32 v[164:165], v[88:89], v[10:11]
	v_add_f32_dpp v142, v121, v121 row_mirror row_mask:0xf bank_mask:0xc bound_ctrl:1
	v_add_f32_dpp v168, v168, v168 quad_perm:[1,0,3,2] row_mask:0xf bank_mask:0xf bound_ctrl:1
	v_pk_fma_f32 v[164:165], v[90:91], v[12:13], v[164:165]
	v_add_f32_dpp v141, v119, v119 row_mirror row_mask:0xf bank_mask:0xc bound_ctrl:1
	v_add_f32_dpp v168, v168, v168 quad_perm:[2,3,0,1] row_mask:0xf bank_mask:0xf bound_ctrl:1
	v_add_f32_e32 v122, v164, v165
	v_add_f32_dpp v149, v142, v142 row_half_mirror row_mask:0xf bank_mask:0x5 bound_ctrl:1
	v_add_f32_dpp v168, v168, v168 row_half_mirror row_mask:0xf bank_mask:0xf bound_ctrl:1
	v_add_f32_dpp v143, v122, v122 row_mirror row_mask:0xf bank_mask:0x3 bound_ctrl:1
	v_add_f32_dpp v148, v141, v141 row_half_mirror row_mask:0xf bank_mask:0xa bound_ctrl:1
	v_add_f32_dpp v168, v168, v168 row_mirror row_mask:0xf bank_mask:0xf bound_ctrl:1
	v_fma_f32 v170, -v114, v168, v107
	v_mul_f32_e32 v170, v115, v170
	v_pk_fma_f32 v[10:11], v[100:101], v[170:171], v[160:161] op_sel_hi:[1,0,1]
	v_pk_fma_f32 v[12:13], v[102:103], v[170:171], v[162:163] op_sel_hi:[1,0,1]
	s_waitcnt lgkmcnt(0)
; #define LAS __attribute__((address_space(3)))
; template <int CTRL> __device__ __forceinline__ float dppf(float x) { return __builtin_bit_cast(float, __builtin_amdgcn_update_dpp(0, __builtin_bit_cast(int, x), CTRL, 0xF, 0xF, true)); }
; __device__ __forceinline__ float red16(float x) { x = red8(x); x += dppf<0x140>(x); return x; }
; __device__ __forceinline__ void gdn_group8(float (&S)[4], float (&pp)[16], int j0, const LAS float* L, int sbase_, int kg, int vl) {
;     typedef RecCfg<1> C;
;     f32x4 q[8], k[8]; f32x2 sc[8]; float v[8];
; #pragma unroll
;     for (int j = 0; j < 8; ++j) { const int s = sbase_ + j;
;         q[j] = *(const LAS f32x4*)(L + C::OFF_Q + s * 64 + kg * 4); k[j] = *(const LAS f32x4*)(L + C::OFF_K + s * 64 + kg * 4);
;         sc[j] = *(const LAS f32x2*)(L + C::OFF_SC + s * 4); v[j] = L[C::OFF_V + s * 32 + vl]; }
;     __builtin_amdgcn_sched_barrier(0);
;     f32x2 s0 = (f32x2){S[0], S[1]}, s1 = (f32x2){S[2], S[3]};
; #pragma unroll
;     for (int j = 0; j < 8; ++j) {
;         const f32x2 k0 = (f32x2){k[j][0], k[j][1]}, k1 = (f32x2){k[j][2], k[j][3]};
;         f32x2 r2 = s0 * k0; r2 = s1 * k1 + r2;
;         const float r = red16(r2.x + r2.y);
;         const float u = sc[j][1] * (v[j] - sc[j][0] * r);
;         const f32x2 uu = (f32x2){u, u}, aa = (f32x2){sc[j][0], sc[j][0]};
;         s0 = s0 * aa + k0 * uu; s1 = s1 * aa + k1 * uu;
;         f32x2 p2 = s0 * (f32x2){q[j][0], q[j][1]}; p2 = s1 * (f32x2){q[j][2], q[j][3]} + p2;
;         pp[j0 + j] = p2.x + p2.y;
;     }
;     S[0] = s0.x; S[1] = s0.y; S[2] = s1.x; S[3] = s1.y;
; }
; __device__ __forceinline__ float reduce_scatter16(const float (&p)[16], int kg) {
;     const bool b3 = kg & 8, b2 = kg & 4, b1 = kg & 2, b0 = kg & 1;
;     float t[8], u[4], w[2];
; #pragma unroll
;     for (int j = 0; j < 8; ++j) { const float keep = b3 ? p[j + 8] : p[j], send = b3 ? p[j] : p[j + 8]; t[j] = keep + dppf<0x140>(send); }
; #pragma unroll
;     for (int j = 0; j < 4; ++j) { const float keep = b2 ? t[j + 4] : t[j], send = b2 ? t[j] : t[j + 4]; u[j] = keep + dppf<0x141>(send); }
; #pragma unroll
;     for (int j = 0; j < 2; ++j) { const float keep = b1 ? u[j + 2] : u[j], send = b1 ? u[j] : u[j + 2]; w[j] = keep + dppf<0x1B>(send); }
;     const float keep = b0 ? w[1] : w[0], send = b0 ? w[0] : w[1];
;     return keep + dppf<0xB1>(send);
; }
	v_pk_mul_f32 v[158:159], v[10:11], v[32:33]
	v_pk_mul_f32 v[160:161], v[10:11], v[64:65] op_sel_hi:[1,0]
	v_pk_fma_f32 v[158:159], v[12:13], v[34:35], v[158:159]
	v_pk_mul_f32 v[162:163], v[12:13], v[64:65] op_sel_hi:[1,0]
	v_add_f32_e32 v168, v158, v159
	v_pk_mul_f32 v[166:167], v[96:97], v[10:11]
	s_nop 0
	v_add_f32_dpp v168, v168, v168 quad_perm:[1,0,3,2] row_mask:0xf bank_mask:0xf bound_ctrl:1
	v_pk_fma_f32 v[166:167], v[98:99], v[12:13], v[166:167]
	ds_read2_b32 v[104:105], v173 offset1:32
	v_add_f32_dpp v168, v168, v168 quad_perm:[2,3,0,1] row_mask:0xf bank_mask:0xf bound_ctrl:1
	v_add_f32_e32 v123, v166, v167
	ds_read2_b32 v[106:107], v173 offset0:64 offset1:96
	v_add_f32_dpp v168, v168, v168 row_half_mirror row_mask:0xf bank_mask:0xf bound_ctrl:1
	ds_read_b128 v[72:75], v172 offset:3072
	ds_read_b128 v[76:79], v172 offset:19456
	v_add_f32_dpp v168, v168, v168 row_mirror row_mask:0xf bank_mask:0xf bound_ctrl:1
	v_fma_f32 v170, -v64, v168, v60
	v_mul_f32_e32 v170, v65, v170
	v_pk_fma_f32 v[10:11], v[32:33], v[170:171], v[160:161] op_sel_hi:[1,0,1]
	v_pk_fma_f32 v[12:13], v[34:35], v[170:171], v[162:163] op_sel_hi:[1,0,1]
	v_pk_mul_f32 v[158:159], v[10:11], v[40:41]
	v_pk_mul_f32 v[160:161], v[10:11], v[66:67] op_sel_hi:[1,0]
	v_pk_fma_f32 v[158:159], v[12:13], v[42:43], v[158:159]
	v_pk_mul_f32 v[162:163], v[12:13], v[66:67] op_sel_hi:[1,0]
	v_add_f32_e32 v168, v158, v159
	v_pk_mul_f32 v[164:165], v[28:29], v[10:11]
	ds_read_b128 v[80:83], v172 offset:3328
	v_add_f32_dpp v168, v168, v168 quad_perm:[1,0,3,2] row_mask:0xf bank_mask:0xf bound_ctrl:1
	v_pk_fma_f32 v[164:165], v[30:31], v[12:13], v[164:165]
	ds_read_b128 v[84:87], v172 offset:19712
	v_add_f32_dpp v168, v168, v168 quad_perm:[2,3,0,1] row_mask:0xf bank_mask:0xf bound_ctrl:1
	v_add_f32_e32 v124, v164, v165
	ds_read_b128 v[88:91], v172 offset:3584
	v_add_f32_dpp v168, v168, v168 row_half_mirror row_mask:0xf bank_mask:0xf bound_ctrl:1
	ds_read_b128 v[92:95], v172 offset:19968
	ds_read_b128 v[96:99], v172 offset:3840
	v_add_f32_dpp v168, v168, v168 row_mirror row_mask:0xf bank_mask:0xf bound_ctrl:1
	v_fma_f32 v170, -v66, v168, v61
	v_mul_f32_e32 v170, v67, v170
	v_pk_fma_f32 v[10:11], v[40:41], v[170:171], v[160:161] op_sel_hi:[1,0,1]
	v_pk_fma_f32 v[12:13], v[42:43], v[170:171], v[162:163] op_sel_hi:[1,0,1]
	v_pk_mul_f32 v[158:159], v[10:11], v[48:49]
	v_pk_mul_f32 v[160:161], v[10:11], v[68:69] op_sel_hi:[1,0]
	v_pk_fma_f32 v[158:159], v[12:13], v[50:51], v[158:159]
	v_pk_mul_f32 v[162:163], v[12:13], v[68:69] op_sel_hi:[1,0]
	v_add_f32_e32 v168, v158, v159
	v_pk_mul_f32 v[166:167], v[36:37], v[10:11]
	ds_read_b128 v[100:103], v172 offset:20224
	v_add_f32_dpp v168, v168, v168 quad_perm:[1,0,3,2] row_mask:0xf bank_mask:0xf bound_ctrl:1
	v_pk_fma_f32 v[166:167], v[38:39], v[12:13], v[166:167]
	ds_read2_b64 v[108:111], v174 offset0:24 offset1:26
	v_add_f32_dpp v168, v168, v168 quad_perm:[2,3,0,1] row_mask:0xf bank_mask:0xf bound_ctrl:1
	v_add_f32_e32 v125, v166, v167
	ds_read2_b64 v[112:115], v174 offset0:28 offset1:30
	v_add_f32_dpp v168, v168, v168 row_half_mirror row_mask:0xf bank_mask:0xf bound_ctrl:1
	v_add_u32_e32 v173, 0x200, v173
	v_add_f32_dpp v144, v124, v124 row_mirror row_mask:0xf bank_mask:0x3 bound_ctrl:1
	v_add_f32_dpp v168, v168, v168 row_mirror row_mask:0xf bank_mask:0xf bound_ctrl:1
	v_fma_f32 v170, -v68, v168, v62
	v_mul_f32_e32 v170, v69, v170
	v_pk_fma_f32 v[10:11], v[48:49], v[170:171], v[160:161] op_sel_hi:[1,0,1]
	v_pk_fma_f32 v[12:13], v[50:51], v[170:171], v[162:163] op_sel_hi:[1,0,1]
	v_pk_mul_f32 v[158:159], v[10:11], v[56:57]
	v_pk_mul_f32 v[160:161], v[10:11], v[70:71] op_sel_hi:[1,0]
	v_pk_fma_f32 v[158:159], v[12:13], v[58:59], v[158:159]
	v_pk_mul_f32 v[162:163], v[12:13], v[70:71] op_sel_hi:[1,0]
	v_add_f32_e32 v168, v158, v159
	v_pk_mul_f32 v[164:165], v[44:45], v[10:11]
	v_add_f32_dpp v143, v123, v123 row_mirror row_mask:0xf bank_mask:0xc bound_ctrl:1
	v_add_f32_dpp v168, v168, v168 quad_perm:[1,0,3,2] row_mask:0xf bank_mask:0xf bound_ctrl:1
	v_pk_fma_f32 v[164:165], v[46:47], v[12:13], v[164:165]
	v_add_f32_dpp v144, v125, v125 row_mirror row_mask:0xf bank_mask:0xc bound_ctrl:1
	v_add_f32_dpp v168, v168, v168 quad_perm:[2,3,0,1] row_mask:0xf bank_mask:0xf bound_ctrl:1
	v_add_f32_e32 v126, v164, v165
	v_add_f32_dpp v149, v143, v143 row_half_mirror row_mask:0xf bank_mask:0xa bound_ctrl:1
	v_add_f32_dpp v168, v168, v168 row_half_mirror row_mask:0xf bank_mask:0xf bound_ctrl:1
	v_add_f32_dpp v145, v126, v126 row_mirror row_mask:0xf bank_mask:0x3 bound_ctrl:1
	v_cndmask_b32_e64 v154, v149, v148, s[48:49]
	v_add_f32_dpp v168, v168, v168 row_mirror row_mask:0xf bank_mask:0xf bound_ctrl:1
	v_fma_f32 v170, -v70, v168, v63
	v_mul_f32_e32 v170, v71, v170
	v_pk_fma_f32 v[10:11], v[56:57], v[170:171], v[160:161] op_sel_hi:[1,0,1]
	v_pk_fma_f32 v[12:13], v[58:59], v[170:171], v[162:163] op_sel_hi:[1,0,1]
	s_waitcnt lgkmcnt(0)
; #define LAS __attribute__((address_space(3)))
; template <int CTRL> __device__ __forceinline__ float dppf(float x) { return __builtin_bit_cast(float, __builtin_amdgcn_update_dpp(0, __builtin_bit_cast(int, x), CTRL, 0xF, 0xF, true)); }
; __device__ __forceinline__ float red16(float x) { x = red8(x); x += dppf<0x140>(x); return x; }
; __device__ __forceinline__ void gdn_group8(float (&S)[4], float (&pp)[16], int j0, const LAS float* L, int sbase_, int kg, int vl) {
;     typedef RecCfg<1> C;
;     f32x4 q[8], k[8]; f32x2 sc[8]; float v[8];
; #pragma unroll
;     for (int j = 0; j < 8; ++j) { const int s = sbase_ + j;
;         q[j] = *(const LAS f32x4*)(L + C::OFF_Q + s * 64 + kg * 4); k[j] = *(const LAS f32x4*)(L + C::OFF_K + s * 64 + kg * 4);
;         sc[j] = *(const LAS f32x2*)(L + C::OFF_SC + s * 4); v[j] = L[C::OFF_V + s * 32 + vl]; }
;     __builtin_amdgcn_sched_barrier(0);
;     f32x2 s0 = (f32x2){S[0], S[1]}, s1 = (f32x2){S[2], S[3]};
; #pragma unroll
;     for (int j = 0; j < 8; ++j) {
;         const f32x2 k0 = (f32x2){k[j][0], k[j][1]}, k1 = (f32x2){k[j][2], k[j][3]};
;         f32x2 r2 = s0 * k0; r2 = s1 * k1 + r2;
;         const float r = red16(r2.x + r2.y);
;         const float u = sc[j][1] * (v[j] - sc[j][0] * r);
;         const f32x2 uu = (f32x2){u, u}, aa = (f32x2){sc[j][0], sc[j][0]};
;         s0 = s0 * aa + k0 * uu; s1 = s1 * aa + k1 * uu;
;         f32x2 p2 = s0 * (f32x2){q[j][0], q[j][1]}; p2 = s1 * (f32x2){q[j][2], q[j][3]} + p2;
;         pp[j0 + j] = p2.x + p2.y;
;     }
;     S[0] = s0.x; S[1] = s0.y; S[2] = s1.x; S[3] = s1.y;
; }
; __device__ __forceinline__ float reduce_scatter16(const float (&p)[16], int kg) {
;     const bool b3 = kg & 8, b2 = kg & 4, b1 = kg & 2, b0 = kg & 1;
;     float t[8], u[4], w[2];
; #pragma unroll
;     for (int j = 0; j < 8; ++j) { const float keep = b3 ? p[j + 8] : p[j], send = b3 ? p[j] : p[j + 8]; t[j] = keep + dppf<0x140>(send); }
; #pragma unroll
;     for (int j = 0; j < 4; ++j) { const float keep = b2 ? t[j + 4] : t[j], send = b2 ? t[j] : t[j + 4]; u[j] = keep + dppf<0x141>(send); }
; #pragma unroll
;     for (int j = 0; j < 2; ++j) { const float keep = b1 ? u[j + 2] : u[j], send = b1 ? u[j] : u[j + 2]; w[j] = keep + dppf<0x1B>(send); }
;     const float keep = b0 ? w[1] : w[0], send = b0 ? w[0] : w[1];
;     return keep + dppf<0xB1>(send);
; }
	v_pk_mul_f32 v[158:159], v[10:11], v[76:77]
	v_pk_mul_f32 v[160:161], v[10:11], v[108:109] op_sel_hi:[1,0]
	v_pk_fma_f32 v[158:159], v[12:13], v[78:79], v[158:159]
	v_pk_mul_f32 v[162:163], v[12:13], v[108:109] op_sel_hi:[1,0]
	v_add_f32_e32 v168, v158, v159
	v_pk_mul_f32 v[166:167], v[52:53], v[10:11]
	v_cndmask_b32_e64 v155, v148, v149, s[48:49]
	v_add_f32_dpp v168, v168, v168 quad_perm:[1,0,3,2] row_mask:0xf bank_mask:0xf bound_ctrl:1
	v_pk_fma_f32 v[166:167], v[54:55], v[12:13], v[166:167]
	ds_read_b128 v[28:31], v172 offset:4096
	v_add_f32_dpp v168, v168, v168 quad_perm:[2,3,0,1] row_mask:0xf bank_mask:0xf bound_ctrl:1
	v_add_f32_e32 v127, v166, v167
	ds_read_b128 v[32:35], v172 offset:20480
	v_add_f32_dpp v168, v168, v168 row_half_mirror row_mask:0xf bank_mask:0xf bound_ctrl:1
	ds_read_b128 v[36:39], v172 offset:4352
	ds_read_b128 v[40:43], v172 offset:20736
	v_add_f32_dpp v168, v168, v168 row_mirror row_mask:0xf bank_mask:0xf bound_ctrl:1
	v_fma_f32 v170, -v108, v168, v104
	v_mul_f32_e32 v170, v109, v170
	v_pk_fma_f32 v[10:11], v[76:77], v[170:171], v[160:161] op_sel_hi:[1,0,1]
	v_pk_fma_f32 v[12:13], v[78:79], v[170:171], v[162:163] op_sel_hi:[1,0,1]
	v_pk_mul_f32 v[158:159], v[10:11], v[84:85]
	v_pk_mul_f32 v[160:161], v[10:11], v[110:111] op_sel_hi:[1,0]
	v_pk_fma_f32 v[158:159], v[12:13], v[86:87], v[158:159]
	v_pk_mul_f32 v[162:163], v[12:13], v[110:111] op_sel_hi:[1,0]
	v_add_f32_e32 v168, v158, v159
	v_pk_mul_f32 v[164:165], v[72:73], v[10:11]
	ds_read_b128 v[44:47], v172 offset:4608
	v_add_f32_dpp v168, v168, v168 quad_perm:[1,0,3,2] row_mask:0xf bank_mask:0xf bound_ctrl:1
	v_pk_fma_f32 v[164:165], v[74:75], v[12:13], v[164:165]
	ds_read_b128 v[48:51], v172 offset:20992
	v_add_f32_dpp v168, v168, v168 quad_perm:[2,3,0,1] row_mask:0xf bank_mask:0xf bound_ctrl:1
	v_add_f32_e32 v128, v164, v165
	ds_read_b128 v[52:55], v172 offset:4864
	v_add_f32_dpp v168, v168, v168 row_half_mirror row_mask:0xf bank_mask:0xf bound_ctrl:1
	ds_read_b128 v[56:59], v172 offset:21248
	ds_read2_b32 v[60:61], v173 offset1:32
	v_add_f32_dpp v168, v168, v168 row_mirror row_mask:0xf bank_mask:0xf bound_ctrl:1
	v_fma_f32 v170, -v110, v168, v105
	v_mul_f32_e32 v170, v111, v170
	v_pk_fma_f32 v[10:11], v[84:85], v[170:171], v[160:161] op_sel_hi:[1,0,1]
	v_pk_fma_f32 v[12:13], v[86:87], v[170:171], v[162:163] op_sel_hi:[1,0,1]
	v_pk_mul_f32 v[158:159], v[10:11], v[92:93]
	v_pk_mul_f32 v[160:161], v[10:11], v[112:113] op_sel_hi:[1,0]
	v_pk_fma_f32 v[158:159], v[12:13], v[94:95], v[158:159]
	v_pk_mul_f32 v[162:163], v[12:13], v[112:113] op_sel_hi:[1,0]
	v_add_f32_e32 v168, v158, v159
	v_pk_mul_f32 v[166:167], v[80:81], v[10:11]
	ds_read2_b32 v[62:63], v173 offset0:64 offset1:96
	v_add_f32_dpp v168, v168, v168 quad_perm:[1,0,3,2] row_mask:0xf bank_mask:0xf bound_ctrl:1
	v_pk_fma_f32 v[166:167], v[82:83], v[12:13], v[166:167]
	ds_read2_b64 v[64:67], v174 offset0:32 offset1:34
	v_add_f32_dpp v168, v168, v168 quad_perm:[2,3,0,1] row_mask:0xf bank_mask:0xf bound_ctrl:1
	v_add_f32_e32 v129, v166, v167
	ds_read2_b64 v[68:71], v174 offset0:36 offset1:38
	v_add_f32_dpp v168, v168, v168 row_half_mirror row_mask:0xf bank_mask:0xf bound_ctrl:1
	v_add_u32_e32 v173, 0x200, v173
	v_add_u32_e32 v172, 0x1000, v172
	v_add_f32_dpp v168, v168, v168 row_mirror row_mask:0xf bank_mask:0xf bound_ctrl:1
	v_fma_f32 v170, -v112, v168, v106
	v_mul_f32_e32 v170, v113, v170
	v_pk_fma_f32 v[10:11], v[92:93], v[170:171], v[160:161] op_sel_hi:[1,0,1]
	v_pk_fma_f32 v[12:13], v[94:95], v[170:171], v[162:163] op_sel_hi:[1,0,1]
	v_pk_mul_f32 v[158:159], v[10:11], v[100:101]
	v_pk_mul_f32 v[160:161], v[10:11], v[114:115] op_sel_hi:[1,0]
	v_pk_fma_f32 v[158:159], v[12:13], v[102:103], v[158:159]
	v_pk_mul_f32 v[162:163], v[12:13], v[114:115] op_sel_hi:[1,0]
	v_add_f32_e32 v168, v158, v159
	v_pk_mul_f32 v[164:165], v[88:89], v[10:11]
	v_add_u32_e32 v174, 0x100, v174
	v_add_f32_dpp v168, v168, v168 quad_perm:[1,0,3,2] row_mask:0xf bank_mask:0xf bound_ctrl:1
	v_pk_fma_f32 v[164:165], v[90:91], v[12:13], v[164:165]
	v_add_f32_dpp v146, v128, v128 row_mirror row_mask:0xf bank_mask:0x3 bound_ctrl:1
	v_add_f32_dpp v168, v168, v168 quad_perm:[2,3,0,1] row_mask:0xf bank_mask:0xf bound_ctrl:1
	v_add_f32_e32 v130, v164, v165
	v_add_f32_dpp v146, v129, v129 row_mirror row_mask:0xf bank_mask:0xc bound_ctrl:1
	v_add_f32_dpp v168, v168, v168 row_half_mirror row_mask:0xf bank_mask:0xf bound_ctrl:1
	v_add_f32_dpp v147, v130, v130 row_mirror row_mask:0xf bank_mask:0x3 bound_ctrl:1
	v_add_f32_dpp v145, v127, v127 row_mirror row_mask:0xf bank_mask:0xc bound_ctrl:1
	v_add_f32_dpp v168, v168, v168 row_mirror row_mask:0xf bank_mask:0xf bound_ctrl:1
	v_fma_f32 v170, -v114, v168, v107
	v_mul_f32_e32 v170, v115, v170
	v_pk_fma_f32 v[10:11], v[100:101], v[170:171], v[160:161] op_sel_hi:[1,0,1]
	v_pk_fma_f32 v[12:13], v[102:103], v[170:171], v[162:163] op_sel_hi:[1,0,1]
	v_pk_mul_f32 v[166:167], v[96:97], v[10:11]
	v_add_f32_dpp v150, v144, v144 row_half_mirror row_mask:0xf bank_mask:0x5 bound_ctrl:1
	v_pk_fma_f32 v[166:167], v[98:99], v[12:13], v[166:167]
	v_add_f32_dpp v151, v146, v146 row_half_mirror row_mask:0xf bank_mask:0x5 bound_ctrl:1
	v_add_f32_e32 v131, v166, v167
	v_add_f32_dpp v152, v155, v154 quad_perm:[3,2,1,0] row_mask:0xf bank_mask:0xf bound_ctrl:1
	v_add_f32_dpp v150, v145, v145 row_half_mirror row_mask:0xf bank_mask:0xa bound_ctrl:1
	v_add_f32_dpp v147, v131, v131 row_mirror row_mask:0xf bank_mask:0xc bound_ctrl:1
	s_nop 1
	v_add_f32_dpp v151, v147, v147 row_half_mirror row_mask:0xf bank_mask:0xa bound_ctrl:1
	v_cndmask_b32_e64 v154, v151, v150, s[48:49]
	v_cndmask_b32_e64 v155, v150, v151, s[48:49]
	s_nop 1
	v_add_f32_dpp v153, v155, v154 quad_perm:[3,2,1,0] row_mask:0xf bank_mask:0xf bound_ctrl:1
	v_cndmask_b32_e64 v154, v153, v152, s[50:51]
	v_cndmask_b32_e64 v155, v152, v153, s[50:51]
	s_nop 1
	v_add_f32_dpp v156, v155, v154 quad_perm:[1,0,3,2] row_mask:0xf bank_mask:0xf bound_ctrl:1
	ds_write_b32 v175, v156
	v_add_u32_e32 v175, 0x800, v175
	s_cmp_eq_u32 s8, 0
	s_cbranch_scc0 .Lgdn_step_loop
	s_waitcnt lgkmcnt(0)
